# recurrence consumer loop phase A: each A-fragment read issued four MFMAs earlier into free VGPRs (S=5 stack)
# baseline (speedup 1.0000x reference)
; __device__ __forceinline__ void delta_rec_task(const Params& P, LAS unsigned char* lds, int b, int h, int tid) {
;     ...
;             bf16x8 SB[8];
; #pragma unroll
;             for (int s = 0; s < 8; ++s) { const int kb = s >> 1, o = 8 * (s & 1); SB[s] = pack8(S[kb][o], S[kb][o + 1], S[kb][o + 2], S[kb][o + 3], S[kb][o + 4], S[kb][o + 5], S[kb][o + 6], S[kb][o + 7]); }
;             f32x16 X1, P1;
; #pragma unroll
;             for (int r = 0; r < 16; ++r) { X1[r] = 0.f; P1[r] = 0.f; }
;             const LAS bf16* KB = (const LAS bf16*)(buf + DR_KB) + n * 136 + 8 * hh; const LAS bf16* QD = (const LAS bf16*)(buf + DR_QD) + n * 136 + 8 * hh;
; #pragma unroll
;             for (int s = 0; s < 8; ++s) { X1 = __builtin_amdgcn_mfma_f32_32x32x16_bf16(*(const LAS bf16x8*)(KB + 16 * s), SB[s], X1, 0, 0, 0);
;                 P1 = __builtin_amdgcn_mfma_f32_32x32x16_bf16(*(const LAS bf16x8*)(QD + 16 * s), SB[s], P1, 0, 0, 0); }
;             const LAS float* VB = (const LAS float*)(buf + DR_VB) + 32 * vb + n;
;             float Y[16];
; #pragma unroll
;             for (int r = 0; r < 16; ++r) Y[r] = VB[((r & 3) + 8 * (r >> 2) + 4 * hh) * 132] - X1[r];
;             const bf16x8 YB0 = pack8(Y[0], Y[1], Y[2], Y[3], Y[4], Y[5], Y[6], Y[7]), YB1 = pack8(Y[8], Y[9], Y[10], Y[11], Y[12], Y[13], Y[14], Y[15]);
;             f32x16 VN;
; #pragma unroll
;             for (int r = 0; r < 16; ++r) VN[r] = 0.f;
;             const LAS bf16* TI = (const LAS bf16*)(buf + DR_TI) + n * 40 + 8 * hh; const LAS bf16* AT = (const LAS bf16*)(buf + DR_AT) + n * 40 + 8 * hh;
;             VN = __builtin_amdgcn_mfma_f32_32x32x16_bf16(*(const LAS bf16x8*)TI, YB0, VN, 0, 0, 0);
;             VN = __builtin_amdgcn_mfma_f32_32x32x16_bf16(*(const LAS bf16x8*)(TI + 16), YB1, VN, 0, 0, 0);
;             const bf16x8 VB0 = pack8(VN[0], VN[1], VN[2], VN[3], VN[4], VN[5], VN[6], VN[7]), VB1 = pack8(VN[8], VN[9], VN[10], VN[11], VN[12], VN[13], VN[14], VN[15]);
;             P1 = __builtin_amdgcn_mfma_f32_32x32x16_bf16(*(const LAS bf16x8*)AT, VB0, P1, 0, 0, 0);
;             P1 = __builtin_amdgcn_mfma_f32_32x32x16_bf16(*(const LAS bf16x8*)(AT + 16), VB1, P1, 0, 0, 0);
;             const float egl = *(const LAS float*)(buf + DR_EGL);
;             const LAS bf16* KDT = (const LAS bf16*)(buf + DR_KDT) + n * 40 + 8 * hh;
; #pragma unroll
;             for (int kb = 0; kb < 4; ++kb) {
; #pragma unroll
.LBB0_1833:
	s_and_b32 s4, s3, 1
	s_mul_i32 s5, s4, 0xc210
	s_add_i32 s5, s5, 0
	v_add3_u32 v136, s5, v117, v118
	ds_read_b128 v[64:67], v136
	ds_read_b128 v[96:99], v136 offset:32
	v_cvt_pk_bf16_f32 v80, v48, v49
	v_cvt_pk_bf16_f32 v81, v50, v51
	v_cvt_pk_bf16_f32 v82, v52, v53
	v_cvt_pk_bf16_f32 v83, v54, v55
	ds_read_b128 v[84:87], v136 offset:8704
	ds_read_b128 v[100:103], v136 offset:8736
	ds_read_b128 v[198:201], v136 offset:64
	ds_read_b128 v[202:205], v136 offset:96
	ds_read_b128 v[206:209], v136 offset:8768
	ds_read_b128 v[210:213], v136 offset:8800
	s_waitcnt lgkmcnt(7)
	v_mfma_f32_32x32x16_bf16 v[64:79], v[64:67], v[80:83], 0
	v_cvt_pk_bf16_f32 v104, v56, v57
	v_cvt_pk_bf16_f32 v105, v58, v59
	v_cvt_pk_bf16_f32 v106, v60, v61
	v_cvt_pk_bf16_f32 v107, v62, v63
	v_cvt_pk_bf16_f32 v108, v32, v33
	v_cvt_pk_bf16_f32 v109, v34, v35
	v_cvt_pk_bf16_f32 v110, v36, v37
	s_waitcnt vmcnt(0) lgkmcnt(5)
	v_mfma_f32_32x32x16_bf16 v[80:95], v[84:87], v[80:83], 0
	v_cvt_pk_bf16_f32 v111, v38, v39
	v_cvt_pk_bf16_f32 v120, v16, v17
	v_cvt_pk_bf16_f32 v121, v18, v19
	v_cvt_pk_bf16_f32 v122, v20, v21
	v_cvt_pk_bf16_f32 v123, v22, v23
	v_lshl_add_u32 v137, v112, 2, s5
	v_add3_u32 v162, v137, v115, v114
	v_mfma_f32_32x32x16_bf16 v[64:79], v[96:99], v[104:107], v[64:79]
	v_cvt_pk_bf16_f32 v96, v40, v41
	v_cvt_pk_bf16_f32 v97, v42, v43
	v_cvt_pk_bf16_f32 v98, v44, v45
	v_cvt_pk_bf16_f32 v99, v46, v47
	v_mov_b32_e32 v144, s5
	v_add3_u32 v161, s5, v119, v118
	v_add_u32_e32 v163, 0x8000, v162
	s_waitcnt lgkmcnt(4)
	v_mfma_f32_32x32x16_bf16 v[80:95], v[100:103], v[104:107], v[80:95]
	ds_read_b128 v[222:225], v136 offset:128
	ds_read_b128 v[226:229], v136 offset:160
	v_add_u32_e32 v164, 0x8400, v162
	v_add_u32_e32 v165, 0x9000, v162
	v_add_u32_e32 v168, 0x9400, v162
	v_add_u32_e32 v169, 0xa000, v162
	v_add_u32_e32 v170, 0xa400, v162
	v_add_u32_e32 v171, 0xb000, v162
	s_waitcnt lgkmcnt(5)
	v_mfma_f32_32x32x16_bf16 v[64:79], v[198:201], v[108:111], v[64:79]
	ds_read_b128 v[230:233], v136 offset:8832
	ds_read_b128 v[234:237], v136 offset:8864
	v_add_u32_e32 v172, 0xb400, v162
	s_mulk_i32 s4, 0x4200
	s_add_i32 s3, s3, 1
	s_cmp_lg_u32 s3, 64
	s_waitcnt lgkmcnt(5)
	v_mfma_f32_32x32x16_bf16 v[80:95], v[206:209], v[108:111], v[80:95]
	v_cvt_pk_bf16_f32 v100, v24, v25
	v_cvt_pk_bf16_f32 v101, v26, v27
	v_cvt_pk_bf16_f32 v102, v28, v29
	v_cvt_pk_bf16_f32 v103, v30, v31
	v_cvt_pk_bf16_f32 v108, v8, v9
	v_cvt_pk_bf16_f32 v109, v10, v11
	v_cvt_pk_bf16_f32 v110, v12, v13
	v_mfma_f32_32x32x16_bf16 v[64:79], v[202:205], v[96:99], v[64:79]
	v_cvt_pk_bf16_f32 v104, v0, v1
	v_cvt_pk_bf16_f32 v105, v2, v3
	v_cvt_pk_bf16_f32 v106, v4, v5
	v_cvt_pk_bf16_f32 v107, v6, v7
	v_cvt_pk_bf16_f32 v111, v14, v15
	s_waitcnt lgkmcnt(4)
	v_mfma_f32_32x32x16_bf16 v[80:95], v[210:213], v[96:99], v[80:95]
	ds_read_b128 v[96:99], v136 offset:8896
	ds_read_b128 v[240:243], v136 offset:192
	s_waitcnt lgkmcnt(5)
	v_mfma_f32_32x32x16_bf16 v[64:79], v[222:225], v[120:123], v[64:79]
	ds_read_b128 v[132:135], v136 offset:224
	ds_read_b128 v[124:127], v136 offset:8928
	s_waitcnt lgkmcnt(6)
	v_mfma_f32_32x32x16_bf16 v[64:79], v[226:229], v[100:103], v[64:79]
	s_waitcnt lgkmcnt(5)
	v_mfma_f32_32x32x16_bf16 v[80:95], v[230:233], v[120:123], v[80:95]
	ds_read_b128 v[136:139], v161 offset:27680
	ds_read_b128 v[140:143], v161 offset:30208
	ds_read_b32 v160, v144 offset:49664
	ds_read_b128 v[144:147], v161 offset:17408
	ds_read_b128 v[148:151], v161 offset:19968
	s_waitcnt lgkmcnt(2)
	v_pk_mul_f32 v[62:63], v[62:63], v[160:161] op_sel_hi:[1,0]
	v_pk_mul_f32 v[60:61], v[60:61], v[160:161] op_sel_hi:[1,0]
	v_mfma_f32_32x32x16_bf16 v[64:79], v[240:243], v[104:107], v[64:79]
	v_mul_f32_e64 v58, v58, v160
	v_mul_f32_e64 v59, v59, v160
	v_mul_f32_e64 v56, v56, v160
	v_mul_f32_e64 v57, v57, v160
	v_mul_f32_e64 v54, v54, v160
	v_mul_f32_e64 v55, v55, v160
	v_pk_mul_f32 v[52:53], v[52:53], v[160:161] op_sel_hi:[1,0]
	v_pk_mul_f32 v[50:51], v[50:51], v[160:161] op_sel_hi:[1,0]
	v_pk_mul_f32 v[48:49], v[48:49], v[160:161] op_sel_hi:[1,0]
	v_pk_mul_f32 v[46:47], v[46:47], v[160:161] op_sel_hi:[1,0]
	v_mfma_f32_32x32x16_bf16 v[80:95], v[234:237], v[100:103], v[80:95]
	ds_read_b128 v[128:131], v161 offset:22528
	ds_read_b128 v[152:155], v161 offset:25088
	ds_read_b128 v[100:103], v161 offset:27648
	ds_read_b128 v[156:159], v161 offset:25120
	ds_read2_b32 v[120:121], v163 offset1:132
	ds_read2_b32 v[122:123], v164 offset0:8 offset1:140
	ds_read2_b32 v[192:193], v165 offset0:32 offset1:164
	ds_read2_b32 v[194:195], v168 offset0:40 offset1:172
	ds_read2_b32 v[196:197], v169 offset0:64 offset1:196
	ds_read2_b32 v[162:163], v170 offset0:72 offset1:204
	ds_read2_b32 v[164:165], v171 offset0:96 offset1:228
	ds_read2_b32 v[168:169], v172 offset0:104 offset1:236
	v_pk_mul_f32 v[44:45], v[44:45], v[160:161] op_sel_hi:[1,0]
	v_pk_mul_f32 v[42:43], v[42:43], v[160:161] op_sel_hi:[1,0]
	v_pk_mul_f32 v[40:41], v[40:41], v[160:161] op_sel_hi:[1,0]
	v_pk_mul_f32 v[38:39], v[38:39], v[160:161] op_sel_hi:[1,0]
	v_pk_mul_f32 v[36:37], v[36:37], v[160:161] op_sel_hi:[1,0]
	v_mfma_f32_32x32x16_bf16 v[64:79], v[132:135], v[108:111], v[64:79]
	v_mul_f32_e64 v34, v34, v160
	v_mul_f32_e64 v35, v35, v160
	v_mul_f32_e64 v32, v32, v160
	v_mul_f32_e64 v33, v33, v160
	v_mul_f32_e64 v30, v30, v160
	v_mul_f32_e64 v31, v31, v160
	v_pk_mul_f32 v[28:29], v[28:29], v[160:161] op_sel_hi:[1,0]
	v_pk_mul_f32 v[26:27], v[26:27], v[160:161] op_sel_hi:[1,0]
	v_pk_mul_f32 v[24:25], v[24:25], v[160:161] op_sel_hi:[1,0]
	v_pk_mul_f32 v[22:23], v[22:23], v[160:161] op_sel_hi:[1,0]
	v_mfma_f32_32x32x16_bf16 v[80:95], v[96:99], v[104:107], v[80:95]
	ds_read_b128 v[176:179], v161 offset:17440
	ds_read_b128 v[180:183], v161 offset:20000
	ds_read_b128 v[184:187], v161 offset:22560
	ds_read_b128 v[188:191], v161 offset:30240
	s_waitcnt lgkmcnt(11)
; #define LAS __attribute__((address_space(3)))
; #define DR_BAR() do { asm volatile("s_waitcnt lgkmcnt(0)" ::: "memory"); __builtin_amdgcn_s_barrier(); asm volatile("" ::: "memory"); } while (0)
; __device__ __forceinline__ void delta_rec_task(const Params& P, LAS unsigned char* lds, int b, int h, int tid) {
;     ...
;             float Y[16];
; #pragma unroll
;             for (int r = 0; r < 16; ++r) Y[r] = VB[((r & 3) + 8 * (r >> 2) + 4 * hh) * 132] - X1[r];
;             const bf16x8 YB0 = pack8(Y[0], Y[1], Y[2], Y[3], Y[4], Y[5], Y[6], Y[7]), YB1 = pack8(Y[8], Y[9], Y[10], Y[11], Y[12], Y[13], Y[14], Y[15]);
;             f32x16 VN;
; #pragma unroll
;             for (int r = 0; r < 16; ++r) VN[r] = 0.f;
;             const LAS bf16* TI = (const LAS bf16*)(buf + DR_TI) + n * 40 + 8 * hh; const LAS bf16* AT = (const LAS bf16*)(buf + DR_AT) + n * 40 + 8 * hh;
;             VN = __builtin_amdgcn_mfma_f32_32x32x16_bf16(*(const LAS bf16x8*)TI, YB0, VN, 0, 0, 0);
;             VN = __builtin_amdgcn_mfma_f32_32x32x16_bf16(*(const LAS bf16x8*)(TI + 16), YB1, VN, 0, 0, 0);
;             const bf16x8 VB0 = pack8(VN[0], VN[1], VN[2], VN[3], VN[4], VN[5], VN[6], VN[7]), VB1 = pack8(VN[8], VN[9], VN[10], VN[11], VN[12], VN[13], VN[14], VN[15]);
;             P1 = __builtin_amdgcn_mfma_f32_32x32x16_bf16(*(const LAS bf16x8*)AT, VB0, P1, 0, 0, 0);
;             P1 = __builtin_amdgcn_mfma_f32_32x32x16_bf16(*(const LAS bf16x8*)(AT + 16), VB1, P1, 0, 0, 0);
;             const float egl = *(const LAS float*)(buf + DR_EGL);
;             const LAS bf16* KDT = (const LAS bf16*)(buf + DR_KDT) + n * 40 + 8 * hh;
; #pragma unroll
;             for (int kb = 0; kb < 4; ++kb) {
; #pragma unroll
;                 for (int r = 0; r < 16; ++r) S[kb][r] *= egl;
;                 S[kb] = __builtin_amdgcn_mfma_f32_32x32x16_bf16(*(const LAS bf16x8*)(KDT + kb * 32 * 40), VB0, S[kb], 0, 0, 0);
;                 S[kb] = __builtin_amdgcn_mfma_f32_32x32x16_bf16(*(const LAS bf16x8*)(KDT + kb * 32 * 40 + 16), VB1, S[kb], 0, 0, 0); }
;             LAS float* op = (LAS float*)(lds + DR_OB) + (c & 1) * 32 * 132 + 4 * hh * 132 + 32 * vb + n;
; #pragma unroll
;             for (int r = 0; r < 16; ++r) op[((r & 3) + 8 * (r >> 2)) * 132] = P1[r];
;             DR_BAR();
	v_pk_add_f32 v[64:65], v[120:121], v[64:65] neg_lo:[0,1] neg_hi:[0,1]
	s_waitcnt lgkmcnt(10)
	v_pk_add_f32 v[66:67], v[122:123], v[66:67] neg_lo:[0,1] neg_hi:[0,1]
	s_waitcnt lgkmcnt(9)
	v_pk_add_f32 v[68:69], v[192:193], v[68:69] neg_lo:[0,1] neg_hi:[0,1]
	s_waitcnt lgkmcnt(8)
	v_pk_add_f32 v[70:71], v[194:195], v[70:71] neg_lo:[0,1] neg_hi:[0,1]
	v_cvt_pk_bf16_f32 v64, v64, v65
	v_cvt_pk_bf16_f32 v65, v66, v67
	v_cvt_pk_bf16_f32 v66, v68, v69
	v_cvt_pk_bf16_f32 v67, v70, v71
	v_mfma_f32_32x32x16_bf16 v[80:95], v[124:127], v[108:111], v[80:95]
	s_waitcnt lgkmcnt(7)
	v_add_f32_e64 v72, v196, -v72
	v_add_f32_e64 v73, v197, -v73
	s_waitcnt lgkmcnt(5)
	v_add_f32_e64 v68, v164, -v76
	v_add_f32_e64 v69, v165, -v77
	s_waitcnt lgkmcnt(4)
	v_pk_add_f32 v[70:71], v[168:169], v[78:79] neg_lo:[0,1] neg_hi:[0,1]
	v_pk_mul_f32 v[20:21], v[20:21], v[160:161] op_sel_hi:[1,0]
	v_pk_mul_f32 v[18:19], v[18:19], v[160:161] op_sel_hi:[1,0]
	v_pk_mul_f32 v[16:17], v[16:17], v[160:161] op_sel_hi:[1,0]
	v_pk_mul_f32 v[14:15], v[14:15], v[160:161] op_sel_hi:[1,0]
	v_mfma_f32_32x32x16_bf16 v[96:111], v[100:103], v[64:67], 0
	v_add_f32_e64 v66, v162, -v74
	v_add_f32_e64 v67, v163, -v75
	v_cvt_pk_bf16_f32 v64, v72, v73
	v_cvt_pk_bf16_f32 v65, v66, v67
	v_cvt_pk_bf16_f32 v66, v68, v69
	v_cvt_pk_bf16_f32 v67, v70, v71
	v_pk_mul_f32 v[12:13], v[12:13], v[160:161] op_sel_hi:[1,0]
	v_pk_mul_f32 v[10:11], v[10:11], v[160:161] op_sel_hi:[1,0]
	v_mfma_f32_32x32x16_bf16 v[96:111], v[136:139], v[64:67], v[96:111]
	v_mul_f32_e64 v8, v8, v160
	v_mul_f32_e64 v9, v9, v160
	v_mul_f32_e64 v6, v6, v160
	v_mul_f32_e64 v7, v7, v160
	v_mul_f32_e64 v4, v4, v160
	v_mul_f32_e64 v5, v5, v160
	v_pk_mul_f32 v[2:3], v[2:3], v[160:161] op_sel_hi:[1,0]
	v_pk_mul_f32 v[0:1], v[0:1], v[160:161] op_sel_hi:[1,0]
	v_add_u32_e32 v72, s4, v116
	v_add_u32_e32 v73, 0x400, v72
	s_nop 1
	v_cvt_pk_bf16_f32 v64, v96, v97
	v_cvt_pk_bf16_f32 v65, v98, v99
	v_cvt_pk_bf16_f32 v66, v100, v101
	v_cvt_pk_bf16_f32 v67, v102, v103
	v_cvt_pk_bf16_f32 v68, v104, v105
	v_cvt_pk_bf16_f32 v69, v106, v107
	v_mfma_f32_32x32x16_bf16 v[48:63], v[144:147], v[64:67], v[48:63]
	v_cvt_pk_bf16_f32 v70, v108, v109
	v_cvt_pk_bf16_f32 v71, v110, v111
	v_add_u32_e32 v74, 0x1000, v72
	v_add_u32_e32 v75, 0x1400, v72
	v_add_u32_e32 v76, 0x2000, v72
	v_add_u32_e32 v77, 0x2400, v72
	v_add_u32_e32 v78, 0x3000, v72
	v_mfma_f32_32x32x16_bf16 v[32:47], v[148:151], v[64:67], v[32:47]
	v_add_u32_e32 v79, 0x3400, v72
	v_mfma_f32_32x32x16_bf16 v[16:31], v[128:131], v[64:67], v[16:31]
	v_mfma_f32_32x32x16_bf16 v[0:15], v[152:155], v[64:67], v[0:15]
	v_mfma_f32_32x32x16_bf16 v[80:95], v[140:143], v[64:67], v[80:95]
	s_waitcnt lgkmcnt(0)
	v_mfma_f32_32x32x16_bf16 v[48:63], v[176:179], v[68:71], v[48:63]
	v_mfma_f32_32x32x16_bf16 v[32:47], v[180:183], v[68:71], v[32:47]
	v_mfma_f32_32x32x16_bf16 v[16:31], v[184:187], v[68:71], v[16:31]
	v_mfma_f32_32x32x16_bf16 v[80:95], v[188:191], v[68:71], v[80:95]
	s_nop 11
	ds_write2_b32 v72, v80, v81 offset1:132
	ds_write2_b32 v73, v82, v83 offset0:8 offset1:140
	ds_write2_b32 v74, v84, v85 offset0:32 offset1:164
	ds_write2_b32 v75, v86, v87 offset0:40 offset1:172
	ds_write2_b32 v76, v88, v89 offset0:64 offset1:196
	ds_write2_b32 v77, v90, v91 offset0:72 offset1:204
	ds_write2_b32 v78, v92, v93 offset0:96 offset1:228
	ds_write2_b32 v79, v94, v95 offset0:104 offset1:236
	v_mfma_f32_32x32x16_bf16 v[0:15], v[156:159], v[68:71], v[0:15]
	s_waitcnt lgkmcnt(0)
	s_barrier
	s_cbranch_scc1 .LBB0_1833
	s_andn2_saveexec_b64 s[6:7], s[6:7]
	s_cbranch_execz .LBB0_1818
